# level-3 scan workgroups no longer wait at barrier 5: they arrive and start as soon as their head's chain tasks and level-1 tasks have published completion counters
# speedup vs baseline: 1.0099x; 1.0099x over previous
.LBB0_634:
	s_or_b64 exec, exec, s[6:7]
	v_cvt_f32_u32_e32 v6, v4
	s_waitcnt vmcnt(0)
	v_readfirstlane_b32 s4, v5
	v_sub_u32_e32 v5, 0, v4
	v_rcp_iflag_f32_e32 v6, v6
	v_add_u32_e32 v7, s4, v3
	v_mul_f32_e32 v6, 0x4f7ffffe, v6
	v_cvt_u32_f32_e32 v6, v6
	v_mul_lo_u32 v3, v5, v6
	v_mul_hi_u32 v3, v6, v3
	v_add_u32_e32 v3, v6, v3
	v_mul_hi_u32 v3, v7, v3
	v_mul_lo_u32 v5, v3, v4
	v_sub_u32_e32 v5, v7, v5
	v_add_u32_e32 v6, 1, v3
	v_cmp_ge_u32_e32 vcc, v5, v4
	s_nop 1
	v_cndmask_b32_e32 v3, v3, v6, vcc
	v_sub_u32_e32 v6, v5, v4
	v_cndmask_b32_e32 v5, v5, v6, vcc
	v_add_u32_e32 v6, 1, v3
	v_cmp_ge_u32_e32 vcc, v5, v4
	v_add_u32_e32 v5, 1, v7
	s_nop 0
	v_cndmask_b32_e32 v3, v3, v6, vcc
	v_mul_lo_u32 v6, v4, v3
	v_add_u32_e32 v4, v6, v4
	v_cmp_ne_u32_e32 vcc, v5, v4
	s_and_saveexec_b64 s[4:5], vcc
	s_xor_b64 s[4:5], exec, s[4:5]
	s_cbranch_execz .LBB0_793
	s_waitcnt lgkmcnt(0)
	v_mov_b32_e32 v2, 0x7000
	buffer_inv sc1
	s_cmpk_gt_u32 s64, 0x7f
	s_branch .Lsplit5_nl
	global_load_dword v2, v2, s[82:83] offset:1280 sc1
	s_add_u32 s10, s82, 0x7500
	s_addc_u32 s11, s83, 0
	s_waitcnt vmcnt(0)
	v_cmp_eq_u32_e32 vcc, v2, v3
	s_and_saveexec_b64 s[6:7], vcc
	s_cbranch_execz .LBB0_792
	s_add_u32 s8, s82, 0x4200
	s_addc_u32 s9, s83, 0
	s_mov_b32 s22, 1
	s_mov_b64 s[12:13], 0
	v_mov_b32_e32 v2, 0
	s_branch .LBB0_638

.LBB0_647:
	s_and_b32 s6, s4, 1
	s_mul_i32 s7, s6, 0xa000
	v_lshl_add_u32 v37, s6, 13, v40
	s_add_i32 s6, s7, 0
	s_add_i32 s7, s6, s8
	s_barrier
	s_add_i32 s6, s6, s9
	v_add_u32_e32 v2, s7, v36
	ds_read_b128 v[18:21], v37
	ds_read_b128 v[42:45], v37 offset:1024
	ds_read_b128 v[22:25], v37 offset:4096
	ds_read_b128 v[46:49], v37 offset:5120
	v_add_u32_e32 v41, s6, v34
	ds_read_b128 v[6:9], v2 offset:32768
	ds_read_b128 v[14:17], v2 offset:32784
	ds_read_b128 v[26:29], v41
	ds_read_b128 v[50:53], v41 offset:1024
	s_and_b32 s6, s5, 0x2000
	s_waitcnt lgkmcnt(3)
	v_lshlrev_b32_e32 v2, 16, v6
	v_and_b32_e32 v3, 0xffff0000, v6
	v_lshlrev_b32_e32 v4, 16, v7
	v_and_b32_e32 v5, 0xffff0000, v7
	v_lshlrev_b32_e32 v6, 16, v8
	v_and_b32_e32 v7, 0xffff0000, v8
	v_lshlrev_b32_e32 v8, 16, v9
	v_and_b32_e32 v9, 0xffff0000, v9
	s_waitcnt lgkmcnt(2)
	v_lshlrev_b32_e32 v10, 16, v14
	v_and_b32_e32 v11, 0xffff0000, v14
	v_lshlrev_b32_e32 v12, 16, v15
	v_and_b32_e32 v13, 0xffff0000, v15
	v_lshlrev_b32_e32 v14, 16, v16
	v_and_b32_e32 v15, 0xffff0000, v16
	v_lshlrev_b32_e32 v16, 16, v17
	v_and_b32_e32 v17, 0xffff0000, v17
	s_add_i32 s4, s4, 1
	s_addk_i32 s5, 0x2000
	s_waitcnt lgkmcnt(1)
	v_mfma_f32_32x32x16_bf16 v[2:17], v[26:29], v[18:21], v[2:17]
	ds_read_b128 v[18:21], v41 offset:4096
	ds_read_b128 v[54:57], v41 offset:5120
	s_cmp_lg_u32 s5, 0x20000
	s_waitcnt lgkmcnt(1)
	v_mfma_f32_32x32x16_bf16 v[18:33], v[18:21], v[22:25], 0
	v_mfma_f32_32x32x16_bf16 v[2:17], v[50:53], v[42:45], v[2:17]
	ds_read_b128 v[42:45], v37 offset:2048
	ds_read_b128 v[50:53], v37 offset:3072
	ds_read_b128 v[58:61], v37 offset:6144
	ds_read_b128 v[62:65], v37 offset:7168
	v_add_u32_e32 v37, s6, v35
	s_waitcnt lgkmcnt(4)
	v_mfma_f32_32x32x16_bf16 v[18:33], v[54:57], v[46:49], v[18:33]
	ds_read_b128 v[46:49], v41 offset:2048
	ds_read_b128 v[54:57], v41 offset:3072
	s_waitcnt lgkmcnt(1)
	v_mfma_f32_32x32x16_bf16 v[2:17], v[46:49], v[42:45], v[2:17]
	ds_read_b128 v[42:45], v41 offset:6144
	ds_read_b128 v[46:49], v41 offset:7168
	s_waitcnt lgkmcnt(1)
	v_mfma_f32_32x32x16_bf16 v[18:33], v[42:45], v[58:61], v[18:33]
	v_mfma_f32_32x32x16_bf16 v[2:17], v[54:57], v[50:53], v[2:17]
	s_waitcnt lgkmcnt(0)
	v_mfma_f32_32x32x16_bf16 v[18:33], v[46:49], v[62:65], v[18:33]
	s_nop 11
	v_pk_add_f32 v[8:9], v[8:9], v[24:25]
	v_pk_add_f32 v[6:7], v[6:7], v[22:23]
	v_pk_add_f32 v[4:5], v[4:5], v[20:21]
	v_pk_add_f32 v[2:3], v[2:3], v[18:19]
	v_pk_add_f32 v[16:17], v[16:17], v[32:33]
	v_pk_add_f32 v[14:15], v[14:15], v[30:31]
	v_pk_add_f32 v[12:13], v[12:13], v[28:29]
	v_pk_add_f32 v[10:11], v[10:11], v[26:27]
	v_cvt_pk_bf16_f32 v2, v2, v3
	v_cvt_pk_bf16_f32 v3, v4, v5
	v_cvt_pk_bf16_f32 v4, v6, v7
	v_cvt_pk_bf16_f32 v5, v8, v9
	v_cvt_pk_bf16_f32 v6, v10, v11
	v_cvt_pk_bf16_f32 v7, v12, v13
	v_cvt_pk_bf16_f32 v8, v14, v15
	v_cvt_pk_bf16_f32 v9, v16, v17
	ds_write_b128 v37, v[2:5]
	ds_write_b128 v37, v[6:9] offset:1024
	global_store_dwordx4 v[38:39], v[2:5], off sc1
	global_store_dwordx4 v[38:39], v[6:9], off offset:16 sc1
	s_waitcnt lgkmcnt(0)
	v_lshl_add_u64 v[38:39], v[38:39], 0, s[2:3]
	s_cbranch_scc1 .LBB0_647
	s_mov_b64 s[2:3], 0

.LBB0_651:
	s_waitcnt vmcnt(0)
	s_waitcnt lgkmcnt(0)
	s_barrier
	s_mov_b64 s[100:101], exec
	v_readlane_b32 s98, v254, 6
	s_nop 3
	s_mov_b32 exec_lo, s98
	s_mov_b32 exec_hi, 0
	s_cbranch_execz .Lchaincnt_join
	v_readlane_b32 s98, v254, 26
	s_nop 3
	s_and_b32 s98, s98, 7
	s_lshr_b32 s98, s98, 1
	s_lshl_b32 s98, s98, 8
	s_add_i32 s98, s98, 0x19000
	v_mov_b32_e32 v2, s98
	v_mov_b32_e32 v3, 1
	global_atomic_add v2, v3, s[82:83]
.Lchaincnt_join:
	s_mov_b64 exec, s[100:101]
	s_mov_b64 s[0:1], -1
	s_branch .LBB0_484

.LBB0_700:
	s_waitcnt vmcnt(0)
	v_cmp_eq_u32_e32 vcc, 0, v0
	s_xor_b64 s[0:1], s[0:1], -1
	s_mov_b64 s[86:87], -1
	s_mov_b64 s[2:3], vcc
	s_mov_b32 s99, s0
	s_waitcnt lgkmcnt(0)
	s_barrier
	s_and_saveexec_b64 s[0:1], s[2:3]
	s_cbranch_execz .LBB0_703
	s_mov_b64 s[2:3], exec
	v_mbcnt_lo_u32_b32 v2, s2, 0
	buffer_wbl2 sc1
	s_waitcnt vmcnt(0)
	s_waitcnt vmcnt(0)
	v_mbcnt_hi_u32_b32 v2, s3, v2
	v_cmp_eq_u32_e32 vcc, 0, v2
	s_and_b64 s[4:5], exec, vcc
	s_mov_b64 exec, s[4:5]
	s_cbranch_execz .LBB0_703
	s_lshl_b32 s4, s47, 6
	s_ashr_i32 s5, s4, 31
	s_lshl_b64 s[4:5], s[4:5], 2
	s_add_u32 s4, s82, s4
	s_addc_u32 s5, s83, s5
	s_bcnt1_i32_b64 s2, s[2:3]
	s_mov_b32 s98, 0x19400
	s_cmp_lg_u32 s99, 0
	s_cselect_b32 s98, 0x18000, s98
	v_mov_b32_e32 v2, s98
	v_mov_b32_e32 v3, s2
	global_atomic_add v2, v3, s[4:5]

.LBB0_796:
	s_or_b64 exec, exec, s[6:7]
	v_cvt_f32_u32_e32 v5, v2
	s_waitcnt vmcnt(0)
	v_readfirstlane_b32 s4, v4
	s_add_u32 s6, s82, 0x7500
	s_addc_u32 s7, s83, 0
	v_rcp_iflag_f32_e32 v5, v5
	v_add_u32_e32 v3, s4, v3
	v_add_u32_e32 v6, 1, v3
	s_mov_b64 s[8:9], -1
	v_mul_f32_e32 v4, 0x4f7ffffe, v5
	v_cvt_u32_f32_e32 v4, v4
	v_sub_u32_e32 v5, 0, v2
	v_mul_lo_u32 v5, v5, v4
	v_mul_hi_u32 v5, v4, v5
	v_add_u32_e32 v4, v4, v5
	v_mul_hi_u32 v4, v3, v4
	v_mul_lo_u32 v5, v4, v2
	v_sub_u32_e32 v3, v3, v5
	v_add_u32_e32 v7, 1, v4
	v_cmp_ge_u32_e32 vcc, v3, v2
	v_sub_u32_e32 v5, v3, v2
	s_nop 0
	v_cndmask_b32_e32 v4, v4, v7, vcc
	v_cndmask_b32_e32 v3, v3, v5, vcc
	v_add_u32_e32 v5, 1, v4
	v_cmp_ge_u32_e32 vcc, v3, v2
	s_nop 1
	v_cndmask_b32_e32 v4, v4, v5, vcc
	v_mul_lo_u32 v3, v2, v4
	v_add_u32_e32 v2, v3, v2
	v_cmp_ne_u32_e32 vcc, v6, v2
	v_mov_b64_e32 v[2:3], s[6:7]
	s_and_saveexec_b64 s[4:5], vcc
	s_cbranch_execz .LBB0_824
	s_mov_b64 s[12:13], 0
	s_cmpk_gt_u32 s64, 0x7f
	s_branch .Lsplit5_ld
	v_mov_b32_e32 v2, 0
	global_load_dword v3, v2, s[6:7] sc1
	s_mov_b64 s[12:13], 0
	s_waitcnt vmcnt(0)
	v_cmp_eq_u32_e32 vcc, v3, v4
	s_and_saveexec_b64 s[10:11], vcc
	s_cbranch_execz .LBB0_823
	s_add_u32 s8, s82, 0x4200
	s_addc_u32 s9, s83, 0
	s_mov_b32 s22, 1
	s_branch .LBB0_800

.LBB0_871:
	s_and_b64 vcc, exec, s[0:1]
	v_readlane_b32 s53, v254, 2
	s_cbranch_vccz .LBB0_900
	s_mov_b64 s[100:101], exec
	v_readlane_b32 s98, v254, 6
	s_nop 3
	s_mov_b32 exec_lo, s98
	s_mov_b32 exec_hi, 0
	s_cbranch_execz .Ll3dep_join
	s_lshr_b32 s98, s64, 5
	s_lshl_b32 s98, s98, 8
	s_add_i32 s99, s98, 0x18000
	s_add_i32 s98, s98, 0x19000
	v_mov_b32_e32 v240, s98
	v_mov_b32_e32 v241, s99
	v_mov_b32_e32 v244, 0
.Ll3dep_spin:
	global_load_dword v242, v240, s[82:83] sc1
	global_load_dword v243, v241, s[82:83] sc1
	global_load_dword v245, v240, s[82:83] offset:1024 sc1
	s_waitcnt vmcnt(0)
	v_add_u32_e32 v244, 1, v244
	v_readfirstlane_b32 s98, v242
	v_readfirstlane_b32 s99, v243
	s_nop 3
	s_cmp_lt_u32 s98, 4
	s_cbranch_scc1 .Ll3dep_more
	s_cmp_lt_u32 s99, 30
	s_cbranch_scc1 .Ll3dep_more
	v_readfirstlane_b32 s98, v245
	s_nop 3
	s_cmp_ge_u32 s98, 2
	s_cbranch_scc1 .Ll3dep_join
.Ll3dep_more:
	s_sleep 1
	v_readfirstlane_b32 s98, v244
	s_nop 3
	s_cmp_lt_u32 s98, 0x40001
	s_cbranch_scc1 .Ll3dep_spin
	v_mov_b32_e32 v242, 1
	v_mov_b32_e32 v243, 0x4000
	global_atomic_add v243, v242, s[82:83] offset:512
	s_waitcnt vmcnt(0)
.Ll3dep_join:
	s_mov_b64 exec, s[100:101]
	s_barrier
	s_ashr_i32 s10, s64, 5
	s_bfe_u32 s49, s64, 0x40001
	s_and_b32 s46, s64, 1
	s_lshl_b32 s47, s46, 3
	s_lshl_b32 s4, s10, 8
	s_lshl_b32 s48, s49, 4
	v_cmp_gt_u32_e32 vcc, 8, v0
	s_and_saveexec_b64 s[0:1], vcc
	s_cbranch_execz .LBB0_874
	s_ashr_i32 s5, s4, 31
	s_lshl_b64 s[2:3], s[4:5], 2
	s_add_u32 s2, s82, s2
	s_addc_u32 s3, s83, s3
	s_lshl_b32 s5, s48, 2
	s_add_u32 s2, s2, s5
	s_addc_u32 s3, s3, 0
	s_lshl_b32 s5, s47, 2
	s_add_u32 s2, s2, s5
	v_lshlrev_b32_e32 v2, 2, v0
	s_addc_u32 s3, s3, 0
	v_mov_b32_e32 v3, 0
	v_lshl_add_u64 v[4:5], s[2:3], 0, v[2:3]
	v_add_co_u32_e32 v4, vcc, 0xb7e000, v4
	v_add_u32_e32 v2, 0, v2
	s_nop 0
	v_addc_co_u32_e32 v5, vcc, 0, v5, vcc
	global_load_dword v3, v[4:5], off
	v_add_u32_e32 v2, 0x24800, v2
	s_waitcnt vmcnt(0)
	ds_write_b32 v2, v3
	s_waitcnt lgkmcnt(0)
